# odd_prep: k_pe/rope-table loads hoisted next to the row loads (one HBM round trip per token instead of two), on top of v50
# speedup vs baseline: 1.0055x; 1.0024x over previous
.LBB0_363:
	s_ashr_i32 s41, s40, 31
	s_mul_i32 s10, s40, 0x1a00
	s_mul_hi_i32 s2, s40, 0x1a00
	s_add_u32 s42, s22, s10
	s_addc_u32 s43, s23, s2
	s_waitcnt lgkmcnt(0)
	global_load_dwordx4 v[6:9], v10, s[42:43]
	global_load_dwordx4 v[12:15], v10, s[42:43] offset:1024
	s_mov_b64 s[54:55], exec
	s_and_b64 exec, exec, s[6:7]
	v_lshl_add_u64 v[28:29], s[42:43], 0, v[0:1]
	v_add_co_u32_e32 v28, vcc, 0x1000, v28
	s_lshl_b64 s[24:25], s[40:41], 8
	s_nop 0
	v_addc_co_u32_e32 v29, vcc, 0, v29, vcc
	v_lshl_add_u64 v[30:31], v[2:3], 0, s[24:25]
	global_load_ushort v24, v[28:29], off offset:2048
	global_load_ushort v25, v[28:29], off offset:2112
	s_nop 0
	global_load_dwordx2 v[26:27], v[30:31], off
	s_mov_b64 exec, s[54:55]
	s_waitcnt vmcnt(4)
	v_and_b32_e32 v21, 0xffff0000, v6
	s_waitcnt vmcnt(0)
	v_and_b32_e32 v20, 0xffff0000, v12
	v_lshlrev_b32_e32 v19, 16, v6
	v_lshlrev_b32_e32 v18, 16, v12
	v_pk_mul_f32 v[20:21], v[20:21], v[20:21]
	v_lshlrev_b32_e32 v23, 16, v7
	v_lshlrev_b32_e32 v22, 16, v13
	v_pk_fma_f32 v[18:19], v[18:19], v[18:19], v[20:21]
	v_and_b32_e32 v7, 0xffff0000, v7
	v_and_b32_e32 v6, 0xffff0000, v13
	v_pk_fma_f32 v[18:19], v[22:23], v[22:23], v[18:19]
	v_lshlrev_b32_e32 v13, 16, v8
	v_lshlrev_b32_e32 v12, 16, v14
	v_pk_fma_f32 v[6:7], v[6:7], v[6:7], v[18:19]
	v_and_b32_e32 v17, 0xffff0000, v9
	v_pk_fma_f32 v[6:7], v[12:13], v[12:13], v[6:7]
	v_and_b32_e32 v13, 0xffff0000, v8
	v_and_b32_e32 v12, 0xffff0000, v14
	v_lshlrev_b32_e32 v9, 16, v9
	v_lshlrev_b32_e32 v8, 16, v15
	v_pk_fma_f32 v[6:7], v[12:13], v[12:13], v[6:7]
	v_and_b32_e32 v16, 0xffff0000, v15
	v_pk_fma_f32 v[6:7], v[8:9], v[8:9], v[6:7]
	s_nop 0
	v_pk_fma_f32 v[6:7], v[16:17], v[16:17], v[6:7]
	s_nop 1
	v_mov_b32_dpp v9, v7 quad_perm:[1,0,3,2] row_mask:0xf bank_mask:0xf bound_ctrl:1
	v_mov_b32_dpp v8, v6 quad_perm:[1,0,3,2] row_mask:0xf bank_mask:0xf bound_ctrl:1
	v_pk_add_f32 v[6:7], v[6:7], v[8:9]
	s_nop 1
	v_mov_b32_dpp v9, v7 quad_perm:[2,3,0,1] row_mask:0xf bank_mask:0xf bound_ctrl:1
	v_mov_b32_dpp v8, v6 quad_perm:[2,3,0,1] row_mask:0xf bank_mask:0xf bound_ctrl:1
	v_pk_add_f32 v[6:7], v[6:7], v[8:9]
	s_nop 1
	v_mov_b32_dpp v9, v7 row_ror:4 row_mask:0xf bank_mask:0xf bound_ctrl:1
	v_mov_b32_dpp v8, v6 row_ror:4 row_mask:0xf bank_mask:0xf bound_ctrl:1
	v_pk_add_f32 v[6:7], v[6:7], v[8:9]
	s_nop 1
	v_mov_b32_dpp v9, v7 row_ror:8 row_mask:0xf bank_mask:0xf bound_ctrl:1
	v_mov_b32_dpp v8, v6 row_ror:8 row_mask:0xf bank_mask:0xf bound_ctrl:1
	v_pk_add_f32 v[6:7], v[6:7], v[8:9]
	ds_bpermute_b32 v9, v207, v7
	ds_bpermute_b32 v8, v207, v6
	s_waitcnt lgkmcnt(0)
	v_pk_add_f32 v[6:7], v[6:7], v[8:9]
	ds_bpermute_b32 v9, v209, v7
	ds_bpermute_b32 v8, v209, v6
	s_and_saveexec_b64 s[54:55], s[0:1]
	s_cbranch_execz .LBB0_365
	s_waitcnt lgkmcnt(0)
	v_pk_add_f32 v[6:7], v[6:7], v[8:9]
	s_mov_b32 s2, 0x3b000000
	v_pk_fma_f32 v[6:7], v[6:7], s[2:3], v[166:167] op_sel_hi:[1,0,0]
	s_mov_b32 s2, 0x800000
	v_mul_f32_e32 v8, 0x4b800000, v7
	v_cmp_gt_f32_e32 vcc, s2, v7
	v_cmp_gt_f32_e64 s[10:11], s2, v6
	s_lshl_b64 s[24:25], s[40:41], 2
	v_cndmask_b32_e32 v7, v7, v8, vcc
	v_rsq_f32_e32 v7, v7
	v_mul_f32_e32 v8, 0x4b800000, v6
	v_cndmask_b32_e64 v6, v6, v8, s[10:11]
	v_rsq_f32_e32 v6, v6
	s_add_u32 s26, s50, s24
	v_mul_f32_e32 v8, 0x45800000, v7
	s_addc_u32 s27, s51, s25
	v_cndmask_b32_e32 v7, v7, v8, vcc
	global_store_dword v1, v7, s[26:27]
	v_mul_f32_e32 v7, 0x45800000, v6
	v_cndmask_b32_e64 v6, v6, v7, s[10:11]
	s_add_u32 s10, s38, s24
	s_addc_u32 s11, s39, s25
	global_store_dword v1, v6, s[10:11]
.LBB0_365:
	s_or_b64 exec, exec, s[54:55]
	s_and_saveexec_b64 s[10:11], s[6:7]
	s_cbranch_execz .LBB0_362
	s_waitcnt lgkmcnt(0)
	s_lshl_b64 s[24:25], s[40:41], 7
	v_lshlrev_b32_e32 v8, 16, v24
	v_lshlrev_b32_e32 v12, 16, v25
	s_nop 0
	v_pk_mul_f32 v[12:13], v[26:27], v[12:13] op_sel:[1,0] op_sel_hi:[0,0]
	v_pk_fma_f32 v[14:15], v[26:27], v[8:9], v[12:13] neg_lo:[0,0,1] neg_hi:[0,0,1]
	v_pk_fma_f32 v[6:7], v[26:27], v[8:9], v[12:13] op_sel_hi:[1,0,1]
	s_nop 0
	v_cvt_pk_bf16_f32 v8, v14, v7
	v_lshl_add_u64 v[6:7], v[4:5], 0, s[24:25]
	global_store_dword v[6:7], v8, off
	s_branch .LBB0_362
